# grid barrier: non-leader workgroups poll the top-level generation word directly instead of a per-XCD generation relayed by the XCD leader (one hop less)
# speedup vs baseline: 1.0961x; 1.0080x over previous
.LBB0_800:
	s_or_b64 exec, exec, s[10:11]
	v_cvt_f32_u32_e32 v4, v2
	s_waitcnt vmcnt(0)
	v_readfirstlane_b32 s8, v3
	v_sub_u32_e32 v3, 0, v2
	v_rcp_iflag_f32_e32 v4, v4
	v_add_u32_e32 v5, s8, v1
	v_mul_f32_e32 v4, 0x4f7ffffe, v4
	v_cvt_u32_f32_e32 v4, v4
	v_mul_lo_u32 v1, v3, v4
	v_mul_hi_u32 v1, v4, v1
	v_add_u32_e32 v1, v4, v1
	v_mul_hi_u32 v1, v5, v1
	v_mul_lo_u32 v3, v1, v2
	v_sub_u32_e32 v3, v5, v3
	v_add_u32_e32 v4, 1, v1
	v_cmp_ge_u32_e32 vcc, v3, v2
	s_nop 1
	v_cndmask_b32_e32 v1, v1, v4, vcc
	v_sub_u32_e32 v4, v3, v2
	v_cndmask_b32_e32 v3, v3, v4, vcc
	v_add_u32_e32 v4, 1, v1
	v_cmp_ge_u32_e32 vcc, v3, v2
	v_add_u32_e32 v3, 1, v5
	s_nop 0
	v_cndmask_b32_e32 v1, v1, v4, vcc
	v_mul_lo_u32 v4, v2, v1
	v_add_u32_e32 v2, v4, v2
	v_cmp_ne_u32_e32 vcc, v3, v2
	s_and_saveexec_b64 s[8:9], vcc
	s_xor_b64 s[8:9], exec, s[8:9]
	s_cbranch_execz .LBB0_814
	s_waitcnt lgkmcnt(0)
	buffer_inv sc1
	s_add_u32 s12, s4, 0x3500
	s_addc_u32 s13, s5, 0
	global_load_dword v0, v129, s[12:13] sc1
	s_waitcnt vmcnt(0)
	v_cmp_eq_u32_e32 vcc, v0, v1
	s_and_saveexec_b64 s[10:11], vcc
	s_cbranch_execz .LBB0_813
	s_mov_b32 s24, 1
	s_mov_b64 s[14:15], 0
	s_branch .LBB0_804
